# Z + attention tile B: the three late, serialised bias-pair LDS reads issued at the top of the tile into free registers (two exposed LDS round trips removed per tile pair)
# baseline (speedup 1.0000x reference)
; #define LAS __attribute__((address_space(3)))
;     ...
;     auto compute = [&](int buf, int t) {
;         const LAS bf16* Ks = (const LAS bf16*)(lds + koff(buf)); const LAS bf16* VT = (const LAS bf16*)(lds + voff(buf));
;         bf16x8 kf[2][4]; float bias[2][2][4];
; #pragma unroll
;         for (int kb = 0; kb < 2; ++kb)
; #pragma unroll
;             for (int ks = 0; ks < 4; ++ks) kf[kb][ks] = *(const LAS bf16x8*)(Ks + (32 * kh + 16 * kb + fr) * QP + 32 * ks + 8 * fq);
;         if (MODE == 0) { const LAS float* bp = BT + (2047 - 16 - (q0 + 32 * rp + fr - t * 64 - 32 * kh - 4 * fq));
; #pragma unroll
;                 for (int kb = 0; kb < 2; ++kb)
; #pragma unroll
;                     for (int i = 0; i < 4; ++i) bias[0][kb][i] = bp[16 * (kb + 1) + i]; }
;     ...
;         if (MODE == 0) { const LAS float* bp = BT + (2047 - 16 - (q0 + 32 * rp + fr - t * 64 - 32 * kh - 4 * fq));
; #pragma unroll
;             for (int kb = 0; kb < 2; ++kb)
; #pragma unroll
;                 for (int i = 0; i < 4; ++i) bias[1][kb][i] = bp[16 * kb + i]; }
.LBB0_121:
	v_pk_add_f32 v[142:143], v[142:143], 0 op_sel_hi:[1,0]
	s_add_i32 s78, s78, 0x9800
	v_pk_add_f32 v[140:141], v[140:141], v[142:143]
	s_cmp_lt_i32 s63, 2
	v_pk_add_f32 v[138:139], v[138:139], v[140:141]
	s_cselect_b32 s63, s78, 0
	v_pk_add_f32 v[136:137], v[136:137], v[138:139]
	s_add_i32 s63, s63, 0
	v_pk_add_f32 v[134:135], v[134:135], v[136:137]
	v_add_u32_e32 v171, s63, v165
	v_pk_add_f32 v[132:133], v[132:133], v[134:135]
	v_add_u32_e32 v182, v171, v167
	v_pk_add_f32 v[130:131], v[130:131], v[132:133]
	v_pk_add_f32 v[128:129], v[128:129], v[130:131]
	v_pk_add_f32 v[150:151], v[150:151], v[128:129]
	ds_read_b128 v[172:175], v182 offset:192
	ds_read_b128 v[192:195], v182 offset:4736
	ds_read_b128 v[196:199], v182 offset:4800
	ds_read2_b32 v[182:183], v170 offset0:80 offset1:81
	ds_read2_b32 v[184:185], v170 offset0:82 offset1:83
	ds_read2_b32 v[188:189], v170 offset0:96 offset1:97
	ds_read2_b32 v[190:191], v170 offset0:98 offset1:99
	ds_read2_b32 v[214:215], v170 offset0:66 offset1:67
	ds_read2_b32 v[216:217], v170 offset0:82 offset1:83
	ds_read2_b32 v[218:219], v170 offset0:80 offset1:81
	s_waitcnt lgkmcnt(10)
	v_mfma_f32_16x16x32_bf16 v[200:203], v[228:231], v[76:79], 0
	v_mfma_f32_16x16x32_bf16 v[204:207], v[232:235], v[76:79], 0
	v_mfma_f32_16x16x32_bf16 v[200:203], v[240:243], v[80:83], v[200:203]
	v_mfma_f32_16x16x32_bf16 v[204:207], v[244:247], v[80:83], v[204:207]
	v_mfma_f32_16x16x32_bf16 v[200:203], v[248:251], v[84:87], v[200:203]
	s_waitcnt lgkmcnt(8)
	v_mfma_f32_16x16x32_bf16 v[204:207], v[192:195], v[84:87], v[204:207]
	v_mfma_f32_16x16x32_bf16 v[200:203], v[172:175], v[88:91], v[200:203]
	s_waitcnt lgkmcnt(7)
	v_mfma_f32_16x16x32_bf16 v[204:207], v[196:199], v[88:91], v[204:207]
	s_add_i32 s68, s41, -2
	s_cmp_ge_u32 s68, s40
	s_cbranch_scc1 .Lstage_b_done
	v_add3_u32 v144, s79, v149, v152
	s_add_i32 s68, s41, -1
	s_cmp_ge_u32 s68, s40
	s_cbranch_scc1 .Lattn_b_short
	s_waitcnt vmcnt(7)
	ds_write_b128 v144, v[48:51]
	s_waitcnt vmcnt(6)
	ds_write_b128 v144, v[52:55] offset:128
	v_add3_u32 v144, s79, v157, v148
	s_waitcnt vmcnt(4)
	s_branch .Lattn_b_join

;     ...
;         auto smax = [&](int rb) {
;             if (MODE == 0) { s[rb][0] = s[rb][0] + (f32x4){bias[rb][0][0], bias[rb][0][1], bias[rb][0][2], bias[rb][0][3]}; s[rb][1] = s[rb][1] + (f32x4){bias[rb][1][0], bias[rb][1][1], bias[rb][1][2], bias[rb][1][3]}; }
;             else { s[rb][0] = s[rb][0] - bref; s[rb][1] = s[rb][1] - bref; }
;             float ps = 0.f;
; #pragma unroll
;             for (int kb = 0; kb < 2; ++kb)
; #pragma unroll
;                 for (int i = 0; i < 4; ++i) { s[rb][kb][i] = __builtin_amdgcn_exp2f(s[rb][kb][i]); ps += s[rb][kb][i]; }
;             lrun[rb] += ps;
;             u32x4 pw; pw.x = pk2(s[rb][0][0], s[rb][0][1]); pw.y = pk2(s[rb][0][2], s[rb][0][3]); pw.z = pk2(s[rb][1][0], s[rb][1][1]); pw.w = pk2(s[rb][1][2], s[rb][1][3]);
;             pf[rb] = __builtin_bit_cast(bf16x8, pw); };
; #pragma unroll
;         for (int ks = 0; ks < 4; ++ks)
; #pragma unroll
;             for (int kb = 0; kb < 2; ++kb) MMA16(kf[kb][ks], qf[0][ks], s[0][kb]);
;         __builtin_amdgcn_sched_barrier(0);
;         bf16x8 vf[8];
; #pragma unroll
;         for (int db = 0; db < 8; ++db) vf[db] = *(const LAS bf16x8*)(VT + (16 * db + fr) * VPA + 32 * kh + 8 * fq);
;         if (MODE == 0) { const LAS float* bp = BT + (2047 - 16 - (q0 + 32 * rp + fr - t * 64 - 32 * kh - 4 * fq));
; #pragma unroll
;             for (int kb = 0; kb < 2; ++kb)
; #pragma unroll
;                 for (int i = 0; i < 4; ++i) bias[1][kb][i] = bp[16 * kb + i]; }
; #pragma unroll
;         for (int ks = 0; ks < 4; ++ks)
; #pragma unroll
;             for (int kb = 0; kb < 2; ++kb) MMA16(kf[kb][ks], qf[1][ks], s[1][kb]);
;         smax(0);
; #pragma unroll
;         for (int g = 0; g < 8; ++g) { __builtin_amdgcn_sched_group_barrier(0x008, 1, 0); __builtin_amdgcn_sched_group_barrier(0x100, 1, 0); __builtin_amdgcn_sched_group_barrier(0x002, 4, 0); }
;         __builtin_amdgcn_sched_barrier(0);
; #pragma unroll
;         for (int db = 0; db < 8; ++db) MMA16(vf[db], pf[0], o[0][db]);
;         smax(1);
; #pragma unroll
;         for (int g = 0; g < 8; ++g) { __builtin_amdgcn_sched_group_barrier(0x008, 1, 1); __builtin_amdgcn_sched_group_barrier(0x002, 4, 1); }
;         __builtin_amdgcn_sched_barrier(0);
; #pragma unroll
;         for (int db = 0; db < 8; ++db) MMA16(vf[db], pf[1], o[1][db]);
;         __builtin_amdgcn_sched_barrier(0);
;     };
.Lstage_b_done:
	v_mfma_f32_16x16x32_bf16 v[208:211], v[228:231], v[92:95], 0
	ds_read2_b32 v[212:213], v170 offset0:64 offset1:65
	v_add3_u32 v171, v171, v168, v169
	s_waitcnt lgkmcnt(6)
	s_nop 1
	v_pk_add_f32 v[184:185], v[184:185], v[202:203]
	v_pk_add_f32 v[182:183], v[182:183], v[200:201]
	s_waitcnt lgkmcnt(1)
	v_pk_add_f32 v[190:191], v[190:191], v[206:207]
	v_mfma_f32_16x16x32_bf16 v[136:139], v[232:235], v[92:95], 0
	ds_read_b128 v[128:131], v171 offset:36352
	v_pk_add_f32 v[188:189], v[188:189], v[204:205]
	v_exp_f32_e32 v207, v182
	v_mfma_f32_16x16x32_bf16 v[200:203], v[240:243], v[96:99], v[208:211]
	ds_read_b128 v[132:135], v171 offset:18432
	v_exp_f32_e32 v183, v183
	v_exp_f32_e32 v185, v185
	v_mfma_f32_16x16x32_bf16 v[144:147], v[244:247], v[96:99], v[136:139]
	v_exp_f32_e32 v209, v184
	v_exp_f32_e32 v211, v188
	v_exp_f32_e32 v189, v189
	ds_read_b128 v[136:139], v171 offset:20992
	v_mfma_f32_16x16x32_bf16 v[200:203], v[248:251], v[100:103], v[200:203]
	ds_read_b128 v[140:143], v171 offset:23552
	v_exp_f32_e32 v191, v191
	v_mfma_f32_16x16x32_bf16 v[192:195], v[192:195], v[100:103], v[144:147]
	s_nop 2
	ds_read_b128 v[144:147], v171 offset:26112
	v_mfma_f32_16x16x32_bf16 v[192:195], v[196:199], v[104:107], v[192:195]
	v_mfma_f32_16x16x32_bf16 v[172:175], v[172:175], v[104:107], v[200:203]
	s_waitcnt lgkmcnt(0)
	s_nop 5
	v_pk_add_f32 v[174:175], v[214:215], v[174:175]
	ds_read_b128 v[196:199], v171 offset:33792
	v_exp_f32_e32 v208, v174
	v_exp_f32_e32 v184, v175
	v_pk_add_f32 v[174:175], v[216:217], v[194:195]
	v_pk_add_f32 v[192:193], v[218:219], v[192:193]
	v_pk_add_f32 v[172:173], v[212:213], v[172:173]
	v_exp_f32_e32 v210, v192
	v_exp_f32_e32 v206, v172
	v_exp_f32_e32 v182, v173
	v_exp_f32_e32 v188, v193
	v_exp_f32_e32 v213, v190
	v_pk_add_f32 v[172:173], v[206:207], 0 op_sel_hi:[1,0]
	v_exp_f32_e32 v212, v174
	v_pk_add_f32 v[172:173], v[182:183], v[172:173]
	v_exp_f32_e32 v190, v175
	v_pk_add_f32 v[172:173], v[208:209], v[172:173]
	ds_read_b128 v[192:195], v171 offset:31232
	v_pk_add_f32 v[172:173], v[184:185], v[172:173]
	s_nop 0
	v_pk_add_f32 v[172:173], v[210:211], v[172:173]
	s_nop 0
	v_pk_add_f32 v[172:173], v[188:189], v[172:173]
	s_nop 0
	v_pk_add_f32 v[172:173], v[212:213], v[172:173]
	s_nop 0
	v_pk_add_f32 v[204:205], v[190:191], v[172:173]
	ds_read_b128 v[172:175], v171 offset:28672
	v_cvt_pk_bf16_f32 v200, v207, v183
	v_cvt_pk_bf16_f32 v201, v209, v185
	v_cvt_pk_bf16_f32 v202, v211, v189
	v_cvt_pk_bf16_f32 v203, v213, v191
	s_nop 0
	v_mfma_f32_16x16x32_bf16 v[124:127], v[132:135], v[200:203], v[124:127]
	v_add_f32_e64 v150, v150, v204
	v_add_f32_e64 v151, v151, v205
	v_cvt_pk_bf16_f32 v204, v206, v182
	v_cvt_pk_bf16_f32 v205, v208, v184
	v_mfma_f32_16x16x32_bf16 v[120:123], v[136:139], v[200:203], v[120:123]
	v_cvt_pk_bf16_f32 v206, v210, v188
	v_cvt_pk_bf16_f32 v207, v212, v190
	v_mfma_f32_16x16x32_bf16 v[116:119], v[140:143], v[200:203], v[116:119]
	v_mfma_f32_16x16x32_bf16 v[112:115], v[144:147], v[200:203], v[112:115]
	s_waitcnt lgkmcnt(0)
	s_mul_i32 s69, s58, 0x9800
	v_add3_u32 v239, s69, v165, v167
	ds_read_b128 v[228:231], v239
	ds_read_b128 v[232:235], v239 offset:4608
	ds_read_b128 v[240:243], v239 offset:64
	ds_read_b128 v[244:247], v239 offset:4672
	ds_read_b128 v[248:251], v239 offset:128
	v_mfma_f32_16x16x32_bf16 v[108:111], v[172:175], v[200:203], v[108:111]
	v_mfma_f32_16x16x32_bf16 v[72:75], v[192:195], v[200:203], v[72:75]
	v_mfma_f32_16x16x32_bf16 v[68:71], v[196:199], v[200:203], v[68:71]
	v_mfma_f32_16x16x32_bf16 v[64:67], v[128:131], v[200:203], v[64:67]
	v_mfma_f32_16x16x32_bf16 v[28:31], v[132:135], v[204:207], v[28:31]
	v_mfma_f32_16x16x32_bf16 v[24:27], v[136:139], v[204:207], v[24:27]
	v_mfma_f32_16x16x32_bf16 v[20:23], v[140:143], v[204:207], v[20:23]
	v_mfma_f32_16x16x32_bf16 v[16:19], v[144:147], v[204:207], v[16:19]
	v_mfma_f32_16x16x32_bf16 v[12:15], v[172:175], v[204:207], v[12:15]
	v_mfma_f32_16x16x32_bf16 v[8:11], v[192:195], v[204:207], v[8:11]
	v_mfma_f32_16x16x32_bf16 v[4:7], v[196:199], v[204:207], v[4:7]
	v_mfma_f32_16x16x32_bf16 v[0:3], v[128:131], v[204:207], v[0:3]
	s_mov_b64 s[68:69], 0x100
	v_lshl_add_u64 v[158:159], v[158:159], 0, s[68:69]
	s_mov_b64 s[68:69], 0x180000
	s_add_i32 s41, s41, 2
	v_lshl_add_u64 v[160:161], v[160:161], 0, s[68:69]
	v_add_u32_e32 v170, 0x200, v170
	s_cmp_ge_u32 s59, s40
	s_mov_b32 s63, s58
	s_barrier
	s_cbranch_scc1 .LBB0_128
